# attention: c=1 waves prefetch K fragments under PV of previous tile; c=0 waves prefetch V fragments under softmax
# baseline (speedup 1.0000x reference)
; #define LAS __attribute__((address_space(3)))
; #define ATT_WAITBAR(N) asm volatile("s_waitcnt vmcnt(" #N ") lgkmcnt(0)\n\ts_barrier" ::: "memory")
; #define ATT_PV(slot) do { bf16x8 va[4], vb[4]; ATT_LDV(va, slot, 0); ATT_SB; ATT_LDV(vb, slot, 1); ATT_SB; ATT_MMV(va, 0); ATT_SB; ATT_LDV(va, slot, 2); ATT_SB; ATT_MMV(vb, 1); ATT_SB; \
;         ATT_LDV(vb, slot, 3); ATT_SB; ATT_MMV(va, 2); ATT_SB; ATT_MMV(vb, 3); ATT_SB; } while (0)
; template <bool NOSHIFT> __device__ __forceinline__ void diff_attn_unit(LAS unsigned char* lds, bf16_t* proj, const bf16_t* VT, int b, int h, int qb, const AttnConsts ac, const float* gsub, const int tid, bf16_t* obuf, int opitch, int ocol) {
;     ...
;     ATT_ISSUE(0); ATT_ISSUE(1);
;     ATT_WAITBAR(4);
;     for (int t = 0; t < NT; ++t) {
;         const int bo = (t & 3) * 16384, sl_cur = bo, sl_prev = ((t - 1) & 3) * 16384;
;         if (t + 2 < NT) ATT_ISSUE(t + 2);
;         const int kv0 = 64 * t;
;         if (c == 1 && t >= 1 && kv0 - 64 <= qmax) ATT_PV(sl_prev);
;         if (kv0 <= qmax) {
;             f32x16 p[2];
;             bf16x8 kf[2][4];
; #pragma unroll
;             for (int mt = 0; mt < 2; ++mt)
; #pragma unroll
;                 for (int ks = 0; ks < 4; ++ks) kf[mt][ks] = *(const LAS bf16x8*)(lds + bo + koff[mt][ks]);
.LBB1_287:
.LBB1_288:
	s_cmp_gt_u32 s47, s83
	s_cselect_b64 s[80:81], -1, 0
	s_or_b64 s[80:81], s[76:77], s[80:81]
	s_and_b64 vcc, exec, s[80:81]
	s_cbranch_vccnz .LBB1_290
	s_add_i32 s15, s14, 0x10000
	s_and_b32 s15, s15, 0xc000
	v_add_u32_e32 v7, s15, v193
	ds_read_b128 v[208:211], v7
	ds_read_b128 v[212:215], v7 offset:4096
	ds_read_b128 v[216:219], v7 offset:8192
	ds_read_b128 v[220:223], v7 offset:12288
	v_add_u32_e32 v7, s15, v204
	ds_read_b128 v[224:227], v7
	ds_read_b128 v[228:231], v7 offset:4096
	ds_read_b128 v[232:235], v7 offset:8192
	ds_read_b128 v[236:239], v7 offset:12288
	s_setprio 1
	s_waitcnt lgkmcnt(7)
	v_mfma_f32_32x32x16_bf16 v[80:95], v[208:211], v[104:107], v[80:95]
	s_waitcnt lgkmcnt(6)
	v_mfma_f32_32x32x16_bf16 v[64:79], v[212:215], v[104:107], v[64:79]
	s_waitcnt lgkmcnt(5)
	v_mfma_f32_32x32x16_bf16 v[48:63], v[216:219], v[104:107], v[48:63]
	s_waitcnt lgkmcnt(4)
	v_mfma_f32_32x32x16_bf16 v[32:47], v[220:223], v[104:107], v[32:47]
	s_setprio 0
	v_add_u32_e32 v7, s15, v205
	ds_read_b128 v[208:211], v7
	ds_read_b128 v[212:215], v7 offset:4096
	ds_read_b128 v[216:219], v7 offset:8192
	ds_read_b128 v[220:223], v7 offset:12288
	s_setprio 1
	s_waitcnt lgkmcnt(7)
	v_mfma_f32_32x32x16_bf16 v[80:95], v[224:227], v[100:103], v[80:95]
	s_waitcnt lgkmcnt(6)
	v_mfma_f32_32x32x16_bf16 v[64:79], v[228:231], v[100:103], v[64:79]
	s_waitcnt lgkmcnt(5)
	v_mfma_f32_32x32x16_bf16 v[48:63], v[232:235], v[100:103], v[48:63]
	s_waitcnt lgkmcnt(4)
	v_mfma_f32_32x32x16_bf16 v[32:47], v[236:239], v[100:103], v[32:47]
	s_setprio 0
	v_add_u32_e32 v7, s15, v206
	ds_read_b128 v[224:227], v7
	ds_read_b128 v[228:231], v7 offset:4096
	ds_read_b128 v[232:235], v7 offset:8192
	ds_read_b128 v[236:239], v7 offset:12288
	s_setprio 1
	s_waitcnt lgkmcnt(7)
	v_mfma_f32_32x32x16_bf16 v[80:95], v[208:211], v[96:99], v[80:95]
	s_waitcnt lgkmcnt(6)
	v_mfma_f32_32x32x16_bf16 v[64:79], v[212:215], v[96:99], v[64:79]
	s_waitcnt lgkmcnt(5)
	v_mfma_f32_32x32x16_bf16 v[48:63], v[216:219], v[96:99], v[48:63]
	s_waitcnt lgkmcnt(4)
	v_mfma_f32_32x32x16_bf16 v[32:47], v[220:223], v[96:99], v[32:47]
	s_setprio 0
	s_addk_i32 s14, 0x4000
	s_cmp_gt_u32 s47, s44
	s_cbranch_scc1 .Latt_c1_noqk
	s_and_b32 s15, s14, 0xc000
	v_add_u32_e32 v7, s15, v179
	v_add_u32_e32 v112, s15, v183
	v_add_u32_e32 v113, s15, v186
	v_add_u32_e32 v114, s15, v187
	ds_read_b128 v[8:11], v7
	ds_read_b128 v[12:15], v7 offset:8192
	ds_read_b128 v[128:131], v112
	ds_read_b128 v[132:135], v112 offset:8192
	ds_read_b128 v[136:139], v113
	ds_read_b128 v[140:143], v113 offset:8192
	ds_read_b128 v[144:147], v114
	ds_read_b128 v[148:151], v114 offset:8192
	s_setprio 1
	s_waitcnt lgkmcnt(11)
	v_mfma_f32_32x32x16_bf16 v[80:95], v[224:227], v[108:111], v[80:95]
	s_waitcnt lgkmcnt(10)
	v_mfma_f32_32x32x16_bf16 v[64:79], v[228:231], v[108:111], v[64:79]
	s_waitcnt lgkmcnt(9)
	v_mfma_f32_32x32x16_bf16 v[48:63], v[232:235], v[108:111], v[48:63]
	s_waitcnt lgkmcnt(8)
	v_mfma_f32_32x32x16_bf16 v[32:47], v[236:239], v[108:111], v[32:47]
	s_setprio 0
	s_branch .Latt_qk_dma
.Latt_c1_noqk:
	s_setprio 1
	s_waitcnt lgkmcnt(3)
	v_mfma_f32_32x32x16_bf16 v[80:95], v[224:227], v[108:111], v[80:95]
	s_waitcnt lgkmcnt(2)
	v_mfma_f32_32x32x16_bf16 v[64:79], v[228:231], v[108:111], v[64:79]
	s_waitcnt lgkmcnt(1)
	v_mfma_f32_32x32x16_bf16 v[48:63], v[232:235], v[108:111], v[48:63]
	s_waitcnt lgkmcnt(0)
	v_mfma_f32_32x32x16_bf16 v[32:47], v[236:239], v[108:111], v[32:47]
	s_setprio 0
	s_branch .LBB1_297

; #define ATT_SB __builtin_amdgcn_sched_barrier(0)
; template <bool NOSHIFT> __device__ __forceinline__ void diff_attn_unit(LAS unsigned char* lds, bf16_t* proj, const bf16_t* VT, int b, int h, int qb, const AttnConsts ac, const float* gsub, const int tid, bf16_t* obuf, int opitch, int ocol) {
;     ...
;             __builtin_amdgcn_s_setprio(1);
; #pragma unroll
;             for (int ks = 0; ks < 4; ++ks)
; #pragma unroll
;                 for (int mt = 0; mt < 2; ++mt) {
;                     if (NOSHIFT && ks == 0) { const f32x16 z = {0.f, 0.f, 0.f, 0.f, 0.f, 0.f, 0.f, 0.f, 0.f, 0.f, 0.f, 0.f, 0.f, 0.f, 0.f, 0.f}; p[mt] = __builtin_amdgcn_mfma_f32_32x32x16_bf16(kf[mt][ks], qf[ks], z, 0, 0, 0); }
;                     else p[mt] = __builtin_amdgcn_mfma_f32_32x32x16_bf16(kf[mt][ks], qf[ks], p[mt], 0, 0, 0);
;                 }
;             __builtin_amdgcn_s_setprio(0);
;             ATT_SB;
;             const bool diag = (t >= 2 * qb);
;             if (diag) {
;                 const int qrel = qrow - kv0 - 8 * hi;
; #pragma unroll
;                 for (int mt = 0; mt < 2; ++mt)
; #pragma unroll
;                     for (int r = 0; r < 16; ++r) { float v = __builtin_amdgcn_exp2f(p[mt][r]); if (32 * mt + 16 * (r >> 3) + (r & 7) > qrel) v = 0.f; p[mt][r] = v; l += v; }
;             } else {
; #pragma unroll
;                 for (int mt = 0; mt < 2; ++mt)
; #pragma unroll
;                     for (int r = 0; r < 16; ++r) { const float v = __builtin_amdgcn_exp2f(p[mt][r]); p[mt][r] = v; l += v; }
.Latt_qk_dma:
	s_and_b64 vcc, exec, s[78:79]
	s_cbranch_vccnz .Latt_nodma
	s_add_i32 s80, s14, 0x8000
	v_lshl_add_u64 v[152:153], s[96:97], 0, v[4:5]
	s_mov_b64 s[16:17], 0x9e82000
	s_and_b32 s80, s80, 0xc000
	v_lshl_add_u64 v[154:155], v[152:153], 0, s[16:17]
	s_add_i32 s81, s80, s59
	s_mov_b32 m0, s81
	v_lshl_add_u64 v[156:157], s[96:97], 0, v[2:3]
	global_load_lds_dwordx4 v[154:155], off
	s_mov_b64 s[16:17], 0x9f42000
	s_addk_i32 s81, 0x2000
	v_lshl_add_u64 v[152:153], v[152:153], 0, s[16:17]
	s_mov_b32 m0, s81
	s_mov_b64 s[16:17], 0x21a00180
	global_load_lds_dwordx4 v[152:153], off
	v_lshl_add_u64 v[158:159], v[156:157], 0, s[16:17]
	s_add_i32 s81, s80, s54
	s_mov_b32 m0, s81
	s_mov_b64 s[16:17], 0x21c00180
	global_load_lds_dwordx4 v[158:159], off
	v_lshl_add_u64 v[156:157], v[156:157], 0, s[16:17]
	s_addk_i32 s81, 0x2000
	s_mov_b32 m0, s81
	s_nop 0
	global_load_lds_dwordx4 v[156:157], off
.Latt_nodma:
	s_setprio 1
	s_waitcnt lgkmcnt(7)
	v_mfma_f32_32x32x16_bf16 v[96:111], v[8:11], v[160:163], 0
	s_waitcnt lgkmcnt(6)
	v_mfma_f32_32x32x16_bf16 v[112:127], v[12:15], v[160:163], 0
	s_waitcnt lgkmcnt(5)
	v_mfma_f32_32x32x16_bf16 v[96:111], v[128:131], v[164:167], v[96:111]
	s_waitcnt lgkmcnt(4)
	v_mfma_f32_32x32x16_bf16 v[112:127], v[132:135], v[164:167], v[112:127]
	s_waitcnt lgkmcnt(3)
	v_mfma_f32_32x32x16_bf16 v[96:111], v[136:139], v[168:171], v[96:111]
	s_waitcnt lgkmcnt(2)
	v_mfma_f32_32x32x16_bf16 v[112:127], v[140:143], v[168:171], v[112:127]
	s_waitcnt lgkmcnt(1)
	v_mfma_f32_32x32x16_bf16 v[96:111], v[144:147], v[172:175], v[96:111]
	s_waitcnt lgkmcnt(0)
	v_mfma_f32_32x32x16_bf16 v[112:127], v[148:151], v[172:175], v[112:127]
	s_setprio 0
	s_andn2_b64 vcc, exec, s[72:73]
	s_cbranch_vccnz .Latt_novpf
	v_add_u32_e32 v8, s15, v193
	v_add_u32_e32 v9, s15, v204
	ds_read_b128 v[208:211], v8
	ds_read_b128 v[212:215], v8 offset:4096
	ds_read_b128 v[216:219], v8 offset:8192
	ds_read_b128 v[220:223], v8 offset:12288
	ds_read_b128 v[224:227], v9
	ds_read_b128 v[228:231], v9 offset:4096
	ds_read_b128 v[232:235], v9 offset:8192
	ds_read_b128 v[236:239], v9 offset:12288
	s_branch .Latt_vpf_done
.Latt_novpf:
	s_nop 8
.Latt_vpf_done:
	v_exp_f32_e32 v96, v96
	v_exp_f32_e32 v97, v97
	v_exp_f32_e32 v98, v98
	v_exp_f32_e32 v99, v99
	v_exp_f32_e32 v100, v100
	v_exp_f32_e32 v101, v101
	v_exp_f32_e32 v102, v102
	v_exp_f32_e32 v103, v103
	v_exp_f32_e32 v104, v104
	v_exp_f32_e32 v105, v105
	v_exp_f32_e32 v106, v106
	v_exp_f32_e32 v107, v107
	v_exp_f32_e32 v108, v108
	v_exp_f32_e32 v109, v109
	v_exp_f32_e32 v110, v110
	v_exp_f32_e32 v111, v111
	v_exp_f32_e32 v112, v112
	v_exp_f32_e32 v113, v113
	v_exp_f32_e32 v114, v114
	v_exp_f32_e32 v115, v115
	v_exp_f32_e32 v116, v116
	v_exp_f32_e32 v117, v117
	v_exp_f32_e32 v118, v118
	v_exp_f32_e32 v119, v119
	v_exp_f32_e32 v120, v120
	v_exp_f32_e32 v121, v121
	v_exp_f32_e32 v122, v122
	v_exp_f32_e32 v123, v123
	v_exp_f32_e32 v124, v124
	v_exp_f32_e32 v125, v125
	v_exp_f32_e32 v126, v126
	v_exp_f32_e32 v127, v127
	s_mov_b64 s[80:81], -1
	s_and_b64 vcc, exec, s[78:79]
	s_cbranch_vccz .LBB1_293
	v_cmp_lt_i32_e32 vcc, -1, v0
	s_mov_b64 s[80:81], 0
	s_nop 0
	v_cndmask_b32_e32 v128, 0, v96, vcc
	v_cmp_lt_i32_e32 vcc, 0, v0
	v_add_f32_e32 v7, v207, v128
	s_nop 0
	v_cndmask_b32_e32 v129, 0, v97, vcc
	v_cmp_lt_i32_e32 vcc, 1, v0
	v_add_f32_e32 v7, v129, v7
	s_nop 0
	v_cndmask_b32_e32 v130, 0, v98, vcc
	v_cmp_lt_i32_e32 vcc, 2, v0
	v_add_f32_e32 v7, v130, v7
	s_nop 0
	v_cndmask_b32_e32 v131, 0, v99, vcc
	v_cmp_lt_i32_e32 vcc, 3, v0
	v_add_f32_e32 v7, v131, v7
	s_nop 0
	v_cndmask_b32_e32 v132, 0, v100, vcc
	v_cmp_lt_i32_e32 vcc, 4, v0
	v_add_f32_e32 v7, v132, v7
	s_nop 0
	v_cndmask_b32_e32 v133, 0, v101, vcc
	v_cmp_lt_i32_e32 vcc, 5, v0
	v_add_f32_e32 v7, v133, v7
	s_nop 0
	v_cndmask_b32_e32 v134, 0, v102, vcc
	v_cmp_lt_i32_e32 vcc, 6, v0
	v_add_f32_e32 v7, v134, v7
	s_nop 0
	v_cndmask_b32_e32 v135, 0, v103, vcc
	v_cmp_lt_i32_e32 vcc, 15, v0
	v_add_f32_e32 v7, v135, v7
	s_nop 0
	v_cndmask_b32_e32 v136, 0, v104, vcc
	v_cmp_lt_i32_e32 vcc, 16, v0
	v_add_f32_e32 v7, v136, v7
	s_nop 0
	v_cndmask_b32_e32 v137, 0, v105, vcc
	v_cmp_lt_i32_e32 vcc, 17, v0
	v_add_f32_e32 v7, v137, v7
	s_nop 0
	v_cndmask_b32_e32 v138, 0, v106, vcc
	v_cmp_lt_i32_e32 vcc, 18, v0
	v_add_f32_e32 v7, v138, v7
	s_nop 0
	v_cndmask_b32_e32 v139, 0, v107, vcc
	v_cmp_lt_i32_e32 vcc, 19, v0
	v_add_f32_e32 v7, v139, v7
	s_nop 0
	v_cndmask_b32_e32 v140, 0, v108, vcc
	v_cmp_lt_i32_e32 vcc, 20, v0
	v_add_f32_e32 v7, v140, v7
	s_nop 0
	v_cndmask_b32_e32 v141, 0, v109, vcc
	v_cmp_lt_i32_e32 vcc, 21, v0
	v_add_f32_e32 v7, v141, v7
	s_nop 0
	v_cndmask_b32_e32 v142, 0, v110, vcc
	v_cmp_lt_i32_e32 vcc, 22, v0
	v_add_f32_e32 v7, v142, v7
	s_nop 0
	v_cndmask_b32_e32 v143, 0, v111, vcc
	v_cmp_lt_i32_e32 vcc, 31, v0
	v_add_f32_e32 v7, v143, v7
	s_nop 0
	v_cndmask_b32_e32 v144, 0, v112, vcc
	v_cmp_lt_i32_e32 vcc, 32, v0
	v_add_f32_e32 v7, v144, v7
	s_nop 0
	v_cndmask_b32_e32 v145, 0, v113, vcc
	v_cmp_lt_i32_e32 vcc, 33, v0
	v_add_f32_e32 v7, v145, v7
	s_nop 0
	v_cndmask_b32_e32 v146, 0, v114, vcc
	v_cmp_lt_i32_e32 vcc, 34, v0
	v_add_f32_e32 v7, v146, v7
	s_nop 0
	v_cndmask_b32_e32 v147, 0, v115, vcc
	v_cmp_lt_i32_e32 vcc, 35, v0
	v_add_f32_e32 v7, v147, v7
	s_nop 0
	v_cndmask_b32_e32 v148, 0, v116, vcc
	v_cmp_lt_i32_e32 vcc, 36, v0
	v_add_f32_e32 v7, v148, v7
	s_nop 0
	v_cndmask_b32_e32 v149, 0, v117, vcc
	v_cmp_lt_i32_e32 vcc, 37, v0
	v_add_f32_e32 v7, v149, v7
	s_nop 0
	v_cndmask_b32_e32 v150, 0, v118, vcc
	v_cmp_lt_i32_e32 vcc, 38, v0
	v_add_f32_e32 v7, v150, v7
	s_nop 0
	v_cndmask_b32_e32 v151, 0, v119, vcc
	v_cmp_lt_i32_e32 vcc, 47, v0
	v_add_f32_e32 v7, v151, v7
	s_nop 0
	v_cndmask_b32_e32 v152, 0, v120, vcc
	v_cmp_lt_i32_e32 vcc, 48, v0
	v_add_f32_e32 v7, v152, v7
	s_nop 0
	v_cndmask_b32_e32 v153, 0, v121, vcc
	v_cmp_lt_i32_e32 vcc, 49, v0
	v_add_f32_e32 v7, v153, v7
	s_nop 0
	v_cndmask_b32_e32 v154, 0, v122, vcc
	v_cmp_lt_i32_e32 vcc, 50, v0
	v_add_f32_e32 v7, v154, v7
	s_nop 0
	v_cndmask_b32_e32 v155, 0, v123, vcc
	v_cmp_lt_i32_e32 vcc, 51, v0
	v_add_f32_e32 v7, v155, v7
	s_nop 0
	v_cndmask_b32_e32 v156, 0, v124, vcc
	v_cmp_lt_i32_e32 vcc, 52, v0
	v_add_f32_e32 v7, v156, v7
	s_nop 0
	v_cndmask_b32_e32 v157, 0, v125, vcc
	v_cmp_lt_i32_e32 vcc, 53, v0
	v_add_f32_e32 v7, v157, v7
	s_nop 0
	v_cndmask_b32_e32 v158, 0, v126, vcc
	v_cmp_lt_i32_e32 vcc, 54, v0
	v_add_f32_e32 v7, v158, v7
	s_nop 0
	v_cndmask_b32_e32 v159, 0, v127, vcc
	v_add_f32_e32 v7, v159, v7

; #define ATT_PV(slot) do { bf16x8 va[4], vb[4]; ATT_LDV(va, slot, 0); ATT_SB; ATT_LDV(vb, slot, 1); ATT_SB; ATT_MMV(va, 0); ATT_SB; ATT_LDV(va, slot, 2); ATT_SB; ATT_MMV(vb, 1); ATT_SB; \
;         ATT_LDV(vb, slot, 3); ATT_SB; ATT_MMV(va, 2); ATT_SB; ATT_MMV(vb, 3); ATT_SB; } while (0)
; template <bool NOSHIFT> __device__ __forceinline__ void diff_attn_unit(LAS unsigned char* lds, bf16_t* proj, const bf16_t* VT, int b, int h, int qb, const AttnConsts ac, const float* gsub, const int tid, bf16_t* obuf, int opitch, int ocol) {
;     ...
;             if (c == 0) ATT_PV(sl_cur);
.Latt_cvt_done:
	s_andn2_b64 vcc, exec, s[72:73]
	s_cbranch_vccnz .LBB1_298
	v_add_u32_e32 v116, s15, v205
	ds_read_b128 v[8:11], v116
	ds_read_b128 v[12:15], v116 offset:4096
	ds_read_b128 v[112:115], v116 offset:8192
	ds_read_b128 v[116:119], v116 offset:12288
	v_add_u32_e32 v132, s15, v206
	ds_read_b128 v[120:123], v132
	ds_read_b128 v[124:127], v132 offset:4096
	ds_read_b128 v[128:131], v132 offset:8192
	ds_read_b128 v[132:135], v132 offset:12288
	s_setprio 1
	s_waitcnt lgkmcnt(8)
	v_mfma_f32_32x32x16_bf16 v[80:95], v[208:211], v[104:107], v[80:95]
	v_mfma_f32_32x32x16_bf16 v[64:79], v[212:215], v[104:107], v[64:79]
	v_mfma_f32_32x32x16_bf16 v[48:63], v[216:219], v[104:107], v[48:63]
	v_mfma_f32_32x32x16_bf16 v[32:47], v[220:223], v[104:107], v[32:47]
	v_mfma_f32_32x32x16_bf16 v[80:95], v[224:227], v[100:103], v[80:95]
	v_mfma_f32_32x32x16_bf16 v[64:79], v[228:231], v[100:103], v[64:79]
	v_mfma_f32_32x32x16_bf16 v[48:63], v[232:235], v[100:103], v[48:63]
	v_mfma_f32_32x32x16_bf16 v[32:47], v[236:239], v[100:103], v[32:47]
	s_waitcnt lgkmcnt(7)
	v_mfma_f32_32x32x16_bf16 v[80:95], v[8:11], v[96:99], v[80:95]
	s_waitcnt lgkmcnt(6)
	v_mfma_f32_32x32x16_bf16 v[64:79], v[12:15], v[96:99], v[64:79]
	s_waitcnt lgkmcnt(5)
	v_mfma_f32_32x32x16_bf16 v[48:63], v[112:115], v[96:99], v[48:63]
	s_waitcnt lgkmcnt(4)
	v_mfma_f32_32x32x16_bf16 v[32:47], v[116:119], v[96:99], v[32:47]
	s_waitcnt lgkmcnt(3)
	v_mfma_f32_32x32x16_bf16 v[80:95], v[120:123], v[108:111], v[80:95]
	s_waitcnt lgkmcnt(2)
	v_mfma_f32_32x32x16_bf16 v[64:79], v[124:127], v[108:111], v[64:79]
	s_waitcnt lgkmcnt(1)
	v_mfma_f32_32x32x16_bf16 v[48:63], v[128:131], v[108:111], v[48:63]
	s_waitcnt lgkmcnt(0)
	v_mfma_f32_32x32x16_bf16 v[32:47], v[132:135], v[108:111], v[32:47]
	s_setprio 0
	s_branch .LBB1_298

; __global__ void __launch_bounds__(512, 2) mega(Args args) {
;     ...
;         if (ph + 1 < args.hi) { if (!(args.flags & FL_XCDBAR) || ph == args.lo) grid.sync(); else xcd_barrier(xbar); }
;     }
; }
.Lpost_getpc0:
	s_add_u32 s98, s98, (.LBB1_9-.Lpost_getpc0)&4294967295
	s_addc_u32 s99, s99, (.LBB1_9-.Lpost_getpc0)>>32
	s_setpc_b64 s[98:99]
.LBB1_793:
	s_endpgm
